# attention tile bodies: removed the six dead VALU instructions per body that computed the lane index for the row-max ds_bpermute (replaced earlier by v_permlane32_swap)
# baseline (speedup 1.0000x reference)
; #define MFMA32(a, b, c) __builtin_amdgcn_mfma_f32_32x32x16_bf16((a), (b), (c), 0, 0, 0)
; template <int DQK, bool WIN>
; DI void attn_item(const u16* __restrict__ Qb, int ldq, const u16* __restrict__ Kb, int ldk, const u16* __restrict__ Vtb, int qb,
;                   float qscale, float sink2, const u16* __restrict__ zb, int ldz, u16* __restrict__ ob, int ldo, u16* lds) {
;     ...
; #pragma unroll
;       for (int kb = 0; kb < 2; ++kb) {
; #pragma unroll
;         for (int i = 0; i < 16; ++i) st[kb][i] = 0.f;
; #pragma unroll
;         for (int s = 0; s < NKS; ++s) {
;           bf16x8 a = *(const bf16x8*)(ks + (kb * 32 + r) * KST + 16 * s + 8 * hh);
;           st[kb] = MFMA32(a, qf[s], st[kb]);
;         }
;       }
;       float mx = -INFINITY;
; #pragma unroll
;       for (int kb = 0; kb < 2; ++kb)
; #pragma unroll
;         for (int i = 0; i < 16; ++i) {
;           float v = st[kb][i];
;           if (MASK) {
;             int kg = k0 + kb * 32 + (i & 3) + 8 * (i >> 2) + 4 * hh;
;             bool ok = kg <= qrow;
;             if (WIN) ok = ok && (qrow - kg < 128);
;             v = ok ? v : -INFINITY;
;             st[kb][i] = v;
;           }
;           mx = fmaxf(mx, v);
;         }
;       mx = fmaxf(mx, __shfl_xor(mx, 32));
;       const float mn = fmaxf(m, mx);
;       if (__any(mn != m)) {
;         const float alpha = __builtin_amdgcn_exp2f((m - mn) * qscale);
;         lsum *= alpha;
; #pragma unroll
;         for (int i = 0; i < 16; ++i) { o[0][i] *= alpha; o[1][i] *= alpha; }
;       }
.LBB0_239:
	s_andn2_b64 vcc, exec, s[24:25]
	s_cbranch_vccnz .LBB0_245
	s_and_saveexec_b64 s[24:25], s[8:9]
	s_cbranch_execz .LBB0_244
	ds_read_b128 v[164:167], v155
	ds_read_b128 v[182:185], v155 offset:32
	ds_read_b128 v[186:189], v155 offset:64
	ds_read_b128 v[190:193], v155 offset:6688
	ds_read_b128 v[194:197], v155 offset:96
	ds_read_b128 v[198:201], v155 offset:128
	ds_read_b128 v[202:205], v155 offset:160
	ds_read_b128 v[206:209], v155 offset:6656
	ds_read_b128 v[210:213], v155 offset:6720
	ds_read_b128 v[214:217], v155 offset:6752
	ds_read_b128 v[218:221], v155 offset:6784
	ds_read_b128 v[222:225], v155 offset:6816
	s_waitcnt lgkmcnt(11)
	v_mfma_f32_32x32x16_bf16 v[50:65], v[164:167], v[66:69], 0
	s_waitcnt lgkmcnt(10)
	v_mfma_f32_32x32x16_bf16 v[50:65], v[182:185], v[70:73], v[50:65]
	s_waitcnt lgkmcnt(9)
	v_mfma_f32_32x32x16_bf16 v[50:65], v[186:189], v[74:77], v[50:65]
	s_waitcnt lgkmcnt(7)
	v_mfma_f32_32x32x16_bf16 v[50:65], v[194:197], v[78:81], v[50:65]
	s_waitcnt lgkmcnt(6)
	v_mfma_f32_32x32x16_bf16 v[50:65], v[198:201], v[82:85], v[50:65]
	s_waitcnt lgkmcnt(5)
	v_mfma_f32_32x32x16_bf16 v[50:65], v[202:205], v[86:89], v[50:65]
	s_waitcnt lgkmcnt(4)
	v_mfma_f32_32x32x16_bf16 v[34:49], v[206:209], v[66:69], 0
	s_nop 8
	s_nop 0
	v_max3_f32 v0, v50, s94, v51
	v_max3_f32 v0, v0, v52, v53
	v_max3_f32 v0, v0, v54, v55
	v_max3_f32 v0, v0, v56, v57
	v_max3_f32 v0, v0, v58, v59
	v_max3_f32 v0, v0, v60, v61
	v_max3_f32 v0, v0, v62, v63
	v_mfma_f32_32x32x16_bf16 v[34:49], v[190:193], v[70:73], v[34:49]
	v_max3_f32 v0, v0, v64, v65
	s_waitcnt lgkmcnt(3)
	v_mfma_f32_32x32x16_bf16 v[34:49], v[210:213], v[74:77], v[34:49]
	s_waitcnt lgkmcnt(2)
	v_mfma_f32_32x32x16_bf16 v[34:49], v[214:217], v[78:81], v[34:49]
	s_waitcnt lgkmcnt(1)
	v_mfma_f32_32x32x16_bf16 v[34:49], v[218:221], v[82:85], v[34:49]
	s_waitcnt lgkmcnt(0)
	v_mfma_f32_32x32x16_bf16 v[34:49], v[222:225], v[86:89], v[34:49]
	s_nop 7
	s_nop 3
	v_max3_f32 v0, v0, v34, v35
	s_nop 2
	v_max3_f32 v0, v0, v36, v37
	s_nop 1
	v_max3_f32 v0, v0, v38, v39
	s_nop 0
	v_max3_f32 v0, v0, v40, v41
	v_max3_f32 v0, v0, v42, v43
	v_max3_f32 v0, v0, v44, v45
	v_max3_f32 v0, v0, v46, v47
	v_max3_f32 v0, v0, v48, v49
	v_mov_b32_e32 v158, v0
	s_nop 1
	v_permlane32_swap_b32 v158, v0
	s_waitcnt lgkmcnt(0)
	v_max3_f32 v0, v157, v0, v158
	v_cmp_neq_f32_e32 vcc, v0, v157
	s_cbranch_vccz .LBB0_243
	v_sub_f32_e32 v157, v157, v0
	v_mul_f32_e32 v157, 0x3e16c740, v157
	v_exp_f32_e32 v158, v157
	s_nop 0
	v_mul_f32_e32 v142, v142, v158
	v_pk_mul_f32 v[32:33], v[32:33], v[158:159] op_sel_hi:[1,0]
	v_pk_mul_f32 v[30:31], v[30:31], v[158:159] op_sel_hi:[1,0]
	v_pk_mul_f32 v[28:29], v[28:29], v[158:159] op_sel_hi:[1,0]
	v_pk_mul_f32 v[26:27], v[26:27], v[158:159] op_sel_hi:[1,0]
	v_pk_mul_f32 v[24:25], v[24:25], v[158:159] op_sel_hi:[1,0]
	v_pk_mul_f32 v[22:23], v[22:23], v[158:159] op_sel_hi:[1,0]
	v_pk_mul_f32 v[20:21], v[20:21], v[158:159] op_sel_hi:[1,0]
	v_pk_mul_f32 v[18:19], v[18:19], v[158:159] op_sel_hi:[1,0]
	v_pk_mul_f32 v[16:17], v[16:17], v[158:159] op_sel_hi:[1,0]
	v_pk_mul_f32 v[14:15], v[14:15], v[158:159] op_sel_hi:[1,0]
	v_pk_mul_f32 v[12:13], v[12:13], v[158:159] op_sel_hi:[1,0]
	v_pk_mul_f32 v[10:11], v[10:11], v[158:159] op_sel_hi:[1,0]
	v_pk_mul_f32 v[8:9], v[8:9], v[158:159] op_sel_hi:[1,0]
	v_pk_mul_f32 v[6:7], v[6:7], v[158:159] op_sel_hi:[1,0]
	v_pk_mul_f32 v[4:5], v[4:5], v[158:159] op_sel_hi:[1,0]
	v_pk_mul_f32 v[2:3], v[2:3], v[158:159] op_sel_hi:[1,0]

; #define MFMA32(a, b, c) __builtin_amdgcn_mfma_f32_32x32x16_bf16((a), (b), (c), 0, 0, 0)
; template <int DQK, bool WIN>
; DI void attn_item(const u16* __restrict__ Qb, int ldq, const u16* __restrict__ Kb, int ldk, const u16* __restrict__ Vtb, int qb,
;                   float qscale, float sink2, const u16* __restrict__ zb, int ldz, u16* __restrict__ ob, int ldo, u16* lds) {
;     ...
; #pragma unroll
;       for (int kb = 0; kb < 2; ++kb) {
; #pragma unroll
;         for (int i = 0; i < 16; ++i) st[kb][i] = 0.f;
; #pragma unroll
;         for (int s = 0; s < NKS; ++s) {
;           bf16x8 a = *(const bf16x8*)(ks + (kb * 32 + r) * KST + 16 * s + 8 * hh);
;           st[kb] = MFMA32(a, qf[s], st[kb]);
;         }
;       }
;       float mx = -INFINITY;
; #pragma unroll
;       for (int kb = 0; kb < 2; ++kb)
; #pragma unroll
;         for (int i = 0; i < 16; ++i) {
;           float v = st[kb][i];
;           if (MASK) {
;             int kg = k0 + kb * 32 + (i & 3) + 8 * (i >> 2) + 4 * hh;
;             bool ok = kg <= qrow;
;             if (WIN) ok = ok && (qrow - kg < 128);
;             v = ok ? v : -INFINITY;
;             st[kb][i] = v;
;           }
;           mx = fmaxf(mx, v);
;         }
;       mx = fmaxf(mx, __shfl_xor(mx, 32));
;       const float mn = fmaxf(m, mx);
;       if (__any(mn != m)) {
;         const float alpha = __builtin_amdgcn_exp2f((m - mn) * qscale);
;         lsum *= alpha;
; #pragma unroll
;         for (int i = 0; i < 16; ++i) { o[0][i] *= alpha; o[1][i] *= alpha; }
;       }
.LBB0_258:
	s_and_saveexec_b64 s[24:25], s[8:9]
	s_cbranch_execz .LBB0_262
	ds_read_b128 v[182:185], v155 offset:22528
	ds_read_b128 v[186:189], v155 offset:22560
	ds_read_b128 v[190:193], v155 offset:22592
	ds_read_b128 v[194:197], v155 offset:29216
	ds_read_b128 v[198:201], v155 offset:22624
	ds_read_b128 v[202:205], v155 offset:22656
	ds_read_b128 v[206:209], v155 offset:22688
	ds_read_b128 v[210:213], v155 offset:29184
	ds_read_b128 v[214:217], v155 offset:29248
	ds_read_b128 v[218:221], v155 offset:29280
	ds_read_b128 v[222:225], v155 offset:29312
	ds_read_b128 v[226:229], v155 offset:29344
	s_nop 7
	s_waitcnt lgkmcnt(11)
	v_mfma_f32_32x32x16_bf16 v[34:49], v[182:185], v[66:69], 0
	s_nop 1
	s_waitcnt lgkmcnt(10)
	v_mfma_f32_32x32x16_bf16 v[34:49], v[186:189], v[70:73], v[34:49]
	s_waitcnt lgkmcnt(9)
	v_mfma_f32_32x32x16_bf16 v[34:49], v[190:193], v[74:77], v[34:49]
	s_waitcnt lgkmcnt(7)
	v_mfma_f32_32x32x16_bf16 v[34:49], v[198:201], v[78:81], v[34:49]
	s_waitcnt lgkmcnt(6)
	v_mfma_f32_32x32x16_bf16 v[34:49], v[202:205], v[82:85], v[34:49]
	s_waitcnt lgkmcnt(5)
	v_mfma_f32_32x32x16_bf16 v[34:49], v[206:209], v[86:89], v[34:49]
	s_waitcnt lgkmcnt(4)
	v_mfma_f32_32x32x16_bf16 v[50:65], v[210:213], v[66:69], 0
	s_nop 8
	s_nop 0
	v_max3_f32 v0, v34, s94, v35
	v_max3_f32 v0, v0, v36, v37
	v_max3_f32 v0, v0, v38, v39
	v_max3_f32 v0, v0, v40, v41
	v_max3_f32 v0, v0, v42, v43
	v_max3_f32 v0, v0, v44, v45
	v_max3_f32 v0, v0, v46, v47
	v_mfma_f32_32x32x16_bf16 v[50:65], v[194:197], v[70:73], v[50:65]
	v_max3_f32 v0, v0, v48, v49
	s_waitcnt lgkmcnt(3)
	v_mfma_f32_32x32x16_bf16 v[50:65], v[214:217], v[74:77], v[50:65]
	s_waitcnt lgkmcnt(2)
	v_mfma_f32_32x32x16_bf16 v[50:65], v[218:221], v[78:81], v[50:65]
	s_waitcnt lgkmcnt(1)
	v_mfma_f32_32x32x16_bf16 v[50:65], v[222:225], v[82:85], v[50:65]
	s_waitcnt lgkmcnt(0)
	v_mfma_f32_32x32x16_bf16 v[50:65], v[226:229], v[86:89], v[50:65]
	s_nop 11
	v_max3_f32 v0, v0, v50, v51
	v_max3_f32 v0, v0, v52, v53
	v_max3_f32 v0, v0, v54, v55
	v_max3_f32 v0, v0, v56, v57
	v_max3_f32 v0, v0, v58, v59
	v_max3_f32 v0, v0, v60, v61
	v_max3_f32 v0, v0, v62, v63
	v_max3_f32 v0, v0, v64, v65
	v_mov_b32_e32 v158, v0
	s_nop 1
	v_permlane32_swap_b32 v158, v0
	s_waitcnt lgkmcnt(0)
	v_max3_f32 v0, v157, v0, v158
	v_cmp_neq_f32_e32 vcc, v0, v157
	s_cbranch_vccz .LBB0_261
	v_sub_f32_e32 v158, v157, v0
	v_mul_f32_e32 v158, 0x3e16c740, v158
	v_exp_f32_e32 v158, v158
	s_nop 0
	v_mul_f32_e32 v142, v142, v158
	v_pk_mul_f32 v[32:33], v[32:33], v[158:159] op_sel_hi:[1,0]
	v_pk_mul_f32 v[30:31], v[30:31], v[158:159] op_sel_hi:[1,0]
	v_pk_mul_f32 v[28:29], v[28:29], v[158:159] op_sel_hi:[1,0]
	v_pk_mul_f32 v[26:27], v[26:27], v[158:159] op_sel_hi:[1,0]
	v_pk_mul_f32 v[24:25], v[24:25], v[158:159] op_sel_hi:[1,0]
	v_pk_mul_f32 v[22:23], v[22:23], v[158:159] op_sel_hi:[1,0]
	v_pk_mul_f32 v[20:21], v[20:21], v[158:159] op_sel_hi:[1,0]
	v_pk_mul_f32 v[18:19], v[18:19], v[158:159] op_sel_hi:[1,0]
	v_pk_mul_f32 v[16:17], v[16:17], v[158:159] op_sel_hi:[1,0]
	v_pk_mul_f32 v[14:15], v[14:15], v[158:159] op_sel_hi:[1,0]
	v_pk_mul_f32 v[12:13], v[12:13], v[158:159] op_sel_hi:[1,0]
	v_pk_mul_f32 v[10:11], v[10:11], v[158:159] op_sel_hi:[1,0]
	v_pk_mul_f32 v[8:9], v[8:9], v[158:159] op_sel_hi:[1,0]
	v_pk_mul_f32 v[6:7], v[6:7], v[158:159] op_sel_hi:[1,0]
	v_pk_mul_f32 v[4:5], v[4:5], v[158:159] op_sel_hi:[1,0]
	v_pk_mul_f32 v[2:3], v[2:3], v[158:159] op_sel_hi:[1,0]

; #define MFMA32(a, b, c) __builtin_amdgcn_mfma_f32_32x32x16_bf16((a), (b), (c), 0, 0, 0)
; template <int DQK, bool WIN>
; DI void attn_item(const u16* __restrict__ Qb, int ldq, const u16* __restrict__ Kb, int ldk, const u16* __restrict__ Vtb, int qb,
;                   float qscale, float sink2, const u16* __restrict__ zb, int ldz, u16* __restrict__ ob, int ldo, u16* lds) {
;     ...
;     bool active = (k0 <= q0 + 31);
;     if (WIN) active = active && (k0 + 63 >= q0 - 127);
;     if (active) {
;       f32x16 st[2];
; #pragma unroll
;       for (int kb = 0; kb < 2; ++kb) {
; #pragma unroll
;         for (int i = 0; i < 16; ++i) st[kb][i] = 0.f;
; #pragma unroll
;         for (int s = 0; s < NKS; ++s) {
;           bf16x8 a = *(const bf16x8*)(ks + (kb * 32 + r) * KST + 16 * s + 8 * hh);
;           st[kb] = MFMA32(a, qf[s], st[kb]);
;         }
;       }
;       float mx = -INFINITY;
; #pragma unroll
;       for (int kb = 0; kb < 2; ++kb)
; #pragma unroll
;         for (int i = 0; i < 16; ++i) {
;           float v = st[kb][i];
;           if (MASK) {
;             int kg = k0 + kb * 32 + (i & 3) + 8 * (i >> 2) + 4 * hh;
;             bool ok = kg <= qrow;
;             if (WIN) ok = ok && (qrow - kg < 128);
;             v = ok ? v : -INFINITY;
;             st[kb][i] = v;
;           }
;           mx = fmaxf(mx, v);
.LBB0_317:
	s_add_i32 s0, s26, 0xffffff40
	v_cmp_le_i32_e32 vcc, s0, v137
	s_add_i32 s0, s26, 0xffffff7f
	v_cmp_ge_i32_e64 s[8:9], s0, v138
	s_and_b64 s[0:1], vcc, s[8:9]
	v_add_u32_e32 v143, s26, v0
	s_and_saveexec_b64 s[34:35], s[0:1]
	s_cbranch_execz .LBB0_321
	ds_read_b128 v[152:155], v139
	ds_read_b128 v[164:167], v139 offset:32
	ds_read_b128 v[182:185], v139 offset:64
	ds_read_b128 v[186:189], v139 offset:4640
	ds_read_b128 v[190:193], v139 offset:96
	ds_read_b128 v[194:197], v139 offset:4608
	ds_read_b128 v[198:201], v139 offset:4672
	ds_read_b128 v[202:205], v139 offset:4704
	v_add_u32_e32 v145, 0xffffff40, v143
	v_cmp_le_i32_e64 s[8:9], v145, v114
	s_movk_i32 s0, 0xff7f
	s_waitcnt lgkmcnt(7)
	v_mfma_f32_32x32x16_bf16 v[50:65], v[152:155], v[66:69], 0
	s_waitcnt lgkmcnt(6)
	v_mfma_f32_32x32x16_bf16 v[50:65], v[164:167], v[70:73], v[50:65]
	s_waitcnt lgkmcnt(5)
	v_mfma_f32_32x32x16_bf16 v[50:65], v[182:185], v[74:77], v[50:65]
	s_waitcnt lgkmcnt(3)
	v_mfma_f32_32x32x16_bf16 v[50:65], v[190:193], v[78:81], v[50:65]
	s_waitcnt lgkmcnt(2)
	v_mfma_f32_32x32x16_bf16 v[34:49], v[194:197], v[66:69], 0
	v_mfma_f32_32x32x16_bf16 v[34:49], v[186:189], v[70:73], v[34:49]
	s_waitcnt lgkmcnt(1)
	v_mfma_f32_32x32x16_bf16 v[34:49], v[198:201], v[74:77], v[34:49]
	s_waitcnt lgkmcnt(0)
	v_mfma_f32_32x32x16_bf16 v[34:49], v[202:205], v[78:81], v[34:49]
	v_add_u32_e32 v146, 59, v141
	v_cmp_gt_i32_e32 vcc, s93, v146
	s_and_b64 vcc, s[8:9], vcc
	v_add_u32_e32 v146, 0xffffff42, v143
	s_nop 0
	v_cndmask_b32_e32 v50, v176, v50, vcc
	v_cmp_lt_i32_e32 vcc, v145, v114
	v_add_u32_e32 v145, s26, v142
	v_add_u32_e32 v145, 0xffffff40, v145
	v_cmp_lt_i32_e64 s[8:9], s0, v145
	s_and_b64 vcc, vcc, s[8:9]
	v_add_u32_e32 v147, 57, v141
	v_cndmask_b32_e32 v51, v176, v51, vcc
	v_cmp_gt_i32_e32 vcc, s93, v147
	v_cmp_le_i32_e64 s[8:9], v146, v114
	s_and_b64 vcc, s[8:9], vcc
	v_add_u32_e32 v146, 0xffffff43, v143
	v_add_u32_e32 v147, 56, v141
	v_cndmask_b32_e32 v52, v176, v52, vcc
	v_cmp_gt_i32_e32 vcc, s93, v147
	v_cmp_le_i32_e64 s[8:9], v146, v114
	s_and_b64 vcc, s[8:9], vcc
	v_add_u32_e32 v146, 0xffffff48, v143
	v_add_u32_e32 v147, 51, v141
	v_cndmask_b32_e32 v53, v176, v53, vcc
	v_cmp_gt_i32_e32 vcc, s93, v147
	v_cmp_le_i32_e64 s[8:9], v146, v114
	s_and_b64 vcc, s[8:9], vcc
	v_cndmask_b32_e32 v148, v176, v54, vcc
	v_add_u32_e32 v54, 0xffffff49, v143
	v_add_u32_e32 v146, 50, v141
	v_cmp_gt_i32_e32 vcc, s93, v146
	v_cmp_le_i32_e64 s[8:9], v54, v114
	v_max3_f32 v145, v50, s94, v51
	s_and_b64 vcc, s[8:9], vcc
	v_max3_f32 v145, v145, v52, v53
	v_cndmask_b32_e32 v147, v176, v55, vcc
	v_max3_f32 v54, v145, v148, v147
	v_add_u32_e32 v55, 0xffffff4a, v143
	v_add_u32_e32 v145, 49, v141
	v_cmp_gt_i32_e32 vcc, s93, v145
	v_cmp_le_i32_e64 s[8:9], v55, v114
	s_and_b64 vcc, s[8:9], vcc
	v_cndmask_b32_e32 v149, v176, v56, vcc
	v_add_u32_e32 v55, 0xffffff4b, v143
	v_add_u32_e32 v56, 48, v141
	v_cmp_gt_i32_e32 vcc, s93, v56
	v_cmp_le_i32_e64 s[8:9], v55, v114
	s_and_b64 vcc, s[8:9], vcc
	v_add_u32_e32 v55, 0xffffff50, v143
	v_add_u32_e32 v56, 43, v141
	v_cndmask_b32_e32 v150, v176, v57, vcc
	v_cmp_gt_i32_e32 vcc, s93, v56
	v_cmp_le_i32_e64 s[8:9], v55, v114
	s_and_b64 vcc, s[8:9], vcc
	v_add_u32_e32 v55, 0xffffff51, v143
	v_add_u32_e32 v56, 42, v141
	v_cndmask_b32_e32 v151, v176, v58, vcc
	v_cmp_gt_i32_e32 vcc, s93, v56
	v_cmp_le_i32_e64 s[8:9], v55, v114
	s_and_b64 vcc, s[8:9], vcc
	v_add_u32_e32 v55, 0xffffff52, v143
	v_add_u32_e32 v56, 41, v141
	v_cndmask_b32_e32 v145, v176, v59, vcc
	v_cmp_gt_i32_e32 vcc, s93, v56
	v_cmp_le_i32_e64 s[8:9], v55, v114
	s_and_b64 vcc, s[8:9], vcc
	v_add_u32_e32 v55, 0xffffff53, v143
	v_add_u32_e32 v56, 40, v141
	v_cndmask_b32_e32 v146, v176, v60, vcc
	v_cmp_gt_i32_e32 vcc, s93, v56
	v_cmp_le_i32_e64 s[8:9], v55, v114
	s_and_b64 vcc, s[8:9], vcc
	v_add_u32_e32 v55, 0xffffff58, v143
	v_add_u32_e32 v56, 35, v141
	v_cndmask_b32_e32 v60, v176, v61, vcc
	v_cmp_gt_i32_e32 vcc, s93, v56
	v_cmp_le_i32_e64 s[8:9], v55, v114
	s_and_b64 vcc, s[8:9], vcc
	v_add_u32_e32 v55, 0xffffff59, v143
	v_add_u32_e32 v56, 34, v141
	v_cndmask_b32_e32 v61, v176, v62, vcc
	v_cmp_gt_i32_e32 vcc, s93, v56
	v_cmp_le_i32_e64 s[8:9], v55, v114
	s_and_b64 vcc, s[8:9], vcc
	v_add_u32_e32 v55, 0xffffff5a, v143
	v_add_u32_e32 v56, 33, v141
	v_cndmask_b32_e32 v58, v176, v63, vcc
	v_cmp_gt_i32_e32 vcc, s93, v56
	v_cmp_le_i32_e64 s[8:9], v55, v114
	v_max3_f32 v54, v54, v149, v150
	s_and_b64 vcc, s[8:9], vcc
	v_add_u32_e32 v55, 0xffffff5b, v143
	v_add_u32_e32 v56, 32, v141
	v_max3_f32 v54, v54, v151, v145
	v_cndmask_b32_e32 v59, v176, v64, vcc
	v_cmp_gt_i32_e32 vcc, s93, v56
	v_cmp_le_i32_e64 s[8:9], v55, v114
	v_max3_f32 v54, v54, v146, v60
	s_and_b64 vcc, s[8:9], vcc
	v_max3_f32 v54, v54, v61, v58
; template <int DQK, bool WIN>
; DI void attn_item(const u16* __restrict__ Qb, int ldq, const u16* __restrict__ Kb, int ldk, const u16* __restrict__ Vtb, int qb,
;                   float qscale, float sink2, const u16* __restrict__ zb, int ldz, u16* __restrict__ ob, int ldo, u16* lds) {
;     ...
;           if (MASK) {
;             int kg = k0 + kb * 32 + (i & 3) + 8 * (i >> 2) + 4 * hh;
;             bool ok = kg <= qrow;
;             if (WIN) ok = ok && (qrow - kg < 128);
;             v = ok ? v : -INFINITY;
;             st[kb][i] = v;
;           }
;           mx = fmaxf(mx, v);
;         }
;       mx = fmaxf(mx, __shfl_xor(mx, 32));
;       const float mn = fmaxf(m, mx);
;       if (__any(mn != m)) {
;         const float alpha = __builtin_amdgcn_exp2f((m - mn) * qscale);
;         lsum *= alpha;
; #pragma unroll
;         for (int i = 0; i < 16; ++i) { o[0][i] *= alpha; o[1][i] *= alpha; }
;       }
	v_cndmask_b32_e32 v56, v176, v65, vcc
	v_max3_f32 v55, v54, v59, v56
	v_add_u32_e32 v54, 0xffffff60, v143
	v_add_u32_e32 v57, 27, v141
	v_cmp_gt_i32_e32 vcc, s93, v57
	v_cmp_le_i32_e64 s[8:9], v54, v114
	s_and_b64 vcc, s[8:9], vcc
	v_cndmask_b32_e32 v57, v176, v34, vcc
	v_add_u32_e32 v34, 0xffffff61, v143
	v_add_u32_e32 v54, 26, v141
	v_cmp_gt_i32_e32 vcc, s93, v54
	v_cmp_le_i32_e64 s[8:9], v34, v114
	s_and_b64 vcc, s[8:9], vcc
	v_cndmask_b32_e32 v54, v176, v35, vcc
	v_max3_f32 v34, v55, v57, v54
	v_add_u32_e32 v35, 0xffffff62, v143
	v_add_u32_e32 v55, 25, v141
	v_cmp_gt_i32_e32 vcc, s93, v55
	v_cmp_le_i32_e64 s[8:9], v35, v114
	s_and_b64 vcc, s[8:9], vcc
	v_cndmask_b32_e32 v55, v176, v36, vcc
	v_add_u32_e32 v35, 0xffffff63, v143
	v_add_u32_e32 v36, 24, v141
	v_cmp_gt_i32_e32 vcc, s93, v36
	v_cmp_le_i32_e64 s[8:9], v35, v114
	s_and_b64 vcc, s[8:9], vcc
	v_cndmask_b32_e32 v36, v176, v37, vcc
	v_add_u32_e32 v35, 0xffffff68, v143
	v_add_u32_e32 v37, 19, v141
	v_cmp_gt_i32_e32 vcc, s93, v37
	v_cmp_le_i32_e64 s[8:9], v35, v114
	s_and_b64 vcc, s[8:9], vcc
	v_cndmask_b32_e32 v37, v176, v38, vcc
	v_add_u32_e32 v35, 0xffffff69, v143
	v_add_u32_e32 v38, 18, v141
	v_cmp_gt_i32_e32 vcc, s93, v38
	v_cmp_le_i32_e64 s[8:9], v35, v114
	s_and_b64 vcc, s[8:9], vcc
	v_cndmask_b32_e32 v35, v176, v39, vcc
	v_add_u32_e32 v38, 0xffffff6a, v143
	v_add_u32_e32 v39, 17, v141
	v_cmp_gt_i32_e32 vcc, s93, v39
	v_cmp_le_i32_e64 s[8:9], v38, v114
	s_and_b64 vcc, s[8:9], vcc
	v_cndmask_b32_e32 v38, v176, v40, vcc
	v_add_u32_e32 v39, 0xffffff6b, v143
	v_add_u32_e32 v40, 16, v141
	v_cmp_gt_i32_e32 vcc, s93, v40
	v_cmp_le_i32_e64 s[8:9], v39, v114
	s_and_b64 vcc, s[8:9], vcc
	v_cndmask_b32_e32 v39, v176, v41, vcc
	v_add_u32_e32 v40, 0xffffff70, v143
	v_add_u32_e32 v41, 11, v141
	v_cmp_gt_i32_e32 vcc, s93, v41
	v_cmp_le_i32_e64 s[8:9], v40, v114
	s_and_b64 vcc, s[8:9], vcc
	v_cndmask_b32_e32 v40, v176, v42, vcc
	v_add_u32_e32 v41, 0xffffff71, v143
	v_add_u32_e32 v42, 10, v141
	v_cmp_gt_i32_e32 vcc, s93, v42
	v_cmp_le_i32_e64 s[8:9], v41, v114
	s_and_b64 vcc, s[8:9], vcc
	v_cndmask_b32_e32 v41, v176, v43, vcc
	v_add_u32_e32 v42, 0xffffff72, v143
	v_add_u32_e32 v43, 9, v141
	v_cmp_gt_i32_e32 vcc, s93, v43
	v_cmp_le_i32_e64 s[8:9], v42, v114
	s_and_b64 vcc, s[8:9], vcc
	v_cndmask_b32_e32 v42, v176, v44, vcc
	v_add_u32_e32 v43, 0xffffff73, v143
	v_add_u32_e32 v44, 8, v141
	v_cmp_gt_i32_e32 vcc, s93, v44
	v_cmp_le_i32_e64 s[8:9], v43, v114
	s_and_b64 vcc, s[8:9], vcc
	v_cndmask_b32_e32 v43, v176, v45, vcc
	v_add_u32_e32 v44, 0xffffff78, v143
	v_add_u32_e32 v45, 3, v141
	v_cmp_gt_i32_e32 vcc, s93, v45
	v_cmp_le_i32_e64 s[8:9], v44, v114
	s_and_b64 vcc, s[8:9], vcc
	v_cndmask_b32_e32 v44, v176, v46, vcc
	v_add_u32_e32 v45, 0xffffff79, v143
	v_add_u32_e32 v46, 2, v141
	v_cmp_gt_i32_e32 vcc, s93, v46
	v_cmp_le_i32_e64 s[8:9], v45, v114
	s_and_b64 vcc, s[8:9], vcc
	v_cndmask_b32_e32 v45, v176, v47, vcc
	v_add_u32_e32 v46, 0xffffff7a, v143
	v_add_u32_e32 v47, 1, v141
	v_cmp_gt_i32_e32 vcc, s93, v47
	v_cmp_le_i32_e64 s[8:9], v46, v114
	s_and_b64 vcc, s[8:9], vcc
	v_add_u32_e32 v47, 0xffffff7b, v143
	v_max3_f32 v34, v34, v55, v36
	v_cndmask_b32_e32 v46, v176, v48, vcc
	v_cmp_gt_i32_e32 vcc, s93, v141
	v_cmp_le_i32_e64 s[8:9], v47, v114
	v_max3_f32 v34, v34, v37, v35
	s_and_b64 vcc, s[8:9], vcc
	v_max3_f32 v34, v34, v38, v39
	v_cndmask_b32_e32 v47, v176, v49, vcc
	v_max3_f32 v34, v34, v40, v41
	v_max3_f32 v34, v34, v42, v43
	v_max3_f32 v34, v34, v44, v45
	v_max3_f32 v34, v34, v46, v47
	v_mov_b32_e32 v48, v34
	s_nop 1
	v_permlane32_swap_b32 v48, v34
	s_waitcnt lgkmcnt(0)
	v_max3_f32 v34, v144, v34, v48
	v_cmp_neq_f32_e32 vcc, v34, v144
	s_cbranch_vccz .LBB0_320
	v_sub_f32_e32 v48, v144, v34
	v_mul_f32_e32 v48, 0x3e38aa3b, v48
	v_exp_f32_e32 v48, v48
	s_nop 0
	v_mul_f32_e32 v116, v116, v48
	v_pk_mul_f32 v[32:33], v[32:33], v[48:49] op_sel_hi:[1,0]
	v_pk_mul_f32 v[30:31], v[30:31], v[48:49] op_sel_hi:[1,0]
	v_pk_mul_f32 v[28:29], v[28:29], v[48:49] op_sel_hi:[1,0]
	v_pk_mul_f32 v[26:27], v[26:27], v[48:49] op_sel_hi:[1,0]
	v_pk_mul_f32 v[24:25], v[24:25], v[48:49] op_sel_hi:[1,0]
	v_pk_mul_f32 v[22:23], v[22:23], v[48:49] op_sel_hi:[1,0]
	v_pk_mul_f32 v[20:21], v[20:21], v[48:49] op_sel_hi:[1,0]
	v_pk_mul_f32 v[18:19], v[18:19], v[48:49] op_sel_hi:[1,0]
	v_pk_mul_f32 v[16:17], v[16:17], v[48:49] op_sel_hi:[1,0]
	v_pk_mul_f32 v[14:15], v[14:15], v[48:49] op_sel_hi:[1,0]
	v_pk_mul_f32 v[12:13], v[12:13], v[48:49] op_sel_hi:[1,0]
	v_pk_mul_f32 v[10:11], v[10:11], v[48:49] op_sel_hi:[1,0]
	v_pk_mul_f32 v[8:9], v[8:9], v[48:49] op_sel_hi:[1,0]
	v_pk_mul_f32 v[6:7], v[6:7], v[48:49] op_sel_hi:[1,0]
	v_pk_mul_f32 v[4:5], v[4:5], v[48:49] op_sel_hi:[1,0]
	v_pk_mul_f32 v[2:3], v[2:3], v[48:49] op_sel_hi:[1,0]

; #define MFMA32(a, b, c) __builtin_amdgcn_mfma_f32_32x32x16_bf16((a), (b), (c), 0, 0, 0)
; template <int DQK, bool WIN>
; DI void attn_item(const u16* __restrict__ Qb, int ldq, const u16* __restrict__ Kb, int ldk, const u16* __restrict__ Vtb, int qb,
;                   float qscale, float sink2, const u16* __restrict__ zb, int ldz, u16* __restrict__ ob, int ldo, u16* lds) {
;     ...
;     bool active = (k0 <= q0 + 31);
;     if (WIN) active = active && (k0 + 63 >= q0 - 127);
;     if (active) {
;       f32x16 st[2];
; #pragma unroll
;       for (int kb = 0; kb < 2; ++kb) {
; #pragma unroll
;         for (int i = 0; i < 16; ++i) st[kb][i] = 0.f;
; #pragma unroll
;         for (int s = 0; s < NKS; ++s) {
;           bf16x8 a = *(const bf16x8*)(ks + (kb * 32 + r) * KST + 16 * s + 8 * hh);
;           st[kb] = MFMA32(a, qf[s], st[kb]);
;         }
;       }
;       float mx = -INFINITY;
; #pragma unroll
;       for (int kb = 0; kb < 2; ++kb)
; #pragma unroll
;         for (int i = 0; i < 16; ++i) {
;           float v = st[kb][i];
;           if (MASK) {
;             int kg = k0 + kb * 32 + (i & 3) + 8 * (i >> 2) + 4 * hh;
;             bool ok = kg <= qrow;
;             if (WIN) ok = ok && (qrow - kg < 128);
;             v = ok ? v : -INFINITY;
;             st[kb][i] = v;
;           }
;           mx = fmaxf(mx, v);
.LBB0_323:
	s_add_i32 s0, s26, 0xffffff80
	v_cmp_le_i32_e32 vcc, s0, v137
	s_add_i32 s0, s26, 0xffffffbf
	v_cmp_ge_i32_e64 s[8:9], s0, v138
	s_and_b64 s[0:1], vcc, s[8:9]
	s_and_saveexec_b64 s[34:35], s[0:1]
	s_cbranch_execz .LBB0_327
	ds_read_b128 v[152:155], v139 offset:18432
	ds_read_b128 v[164:167], v139 offset:18464
	ds_read_b128 v[182:185], v139 offset:18496
	ds_read_b128 v[186:189], v139 offset:23072
	ds_read_b128 v[190:193], v139 offset:18528
	ds_read_b128 v[194:197], v139 offset:23040
	ds_read_b128 v[198:201], v139 offset:23104
	ds_read_b128 v[202:205], v139 offset:23136
	v_add_u32_e32 v145, 0xffffff80, v143
	v_cmp_le_i32_e64 s[8:9], v145, v114
	v_add_u32_e32 v145, 0xffffff81, v143
	s_waitcnt lgkmcnt(7)
	v_mfma_f32_32x32x16_bf16 v[50:65], v[152:155], v[66:69], 0
	s_waitcnt lgkmcnt(6)
	v_mfma_f32_32x32x16_bf16 v[50:65], v[164:167], v[70:73], v[50:65]
	s_waitcnt lgkmcnt(5)
	v_mfma_f32_32x32x16_bf16 v[50:65], v[182:185], v[74:77], v[50:65]
	s_waitcnt lgkmcnt(3)
	v_mfma_f32_32x32x16_bf16 v[50:65], v[190:193], v[78:81], v[50:65]
	s_waitcnt lgkmcnt(2)
	v_mfma_f32_32x32x16_bf16 v[34:49], v[194:197], v[66:69], 0
	v_mfma_f32_32x32x16_bf16 v[34:49], v[186:189], v[70:73], v[34:49]
	s_waitcnt lgkmcnt(1)
	v_mfma_f32_32x32x16_bf16 v[34:49], v[198:201], v[74:77], v[34:49]
	s_waitcnt lgkmcnt(0)
	v_mfma_f32_32x32x16_bf16 v[34:49], v[202:205], v[78:81], v[34:49]
	v_add_u32_e32 v146, -5, v141
	v_cmp_gt_i32_e32 vcc, s93, v146
	s_and_b64 vcc, s[8:9], vcc
	v_add_u32_e32 v146, -6, v141
	s_nop 0
	v_cndmask_b32_e32 v50, v176, v50, vcc
	v_cmp_gt_i32_e32 vcc, s93, v146
	v_cmp_le_i32_e64 s[8:9], v145, v114
	s_and_b64 vcc, s[8:9], vcc
	v_add_u32_e32 v146, 0xffffff82, v143
	v_add_u32_e32 v147, -7, v141
	v_cndmask_b32_e32 v51, v176, v51, vcc
	v_cmp_gt_i32_e32 vcc, s93, v147
	v_cmp_le_i32_e64 s[8:9], v146, v114
	s_and_b64 vcc, s[8:9], vcc
	v_add_u32_e32 v146, 0xffffff83, v143
	v_add_u32_e32 v147, -8, v141
	v_cndmask_b32_e32 v52, v176, v52, vcc
	v_cmp_gt_i32_e32 vcc, s93, v147
	v_cmp_le_i32_e64 s[8:9], v146, v114
	s_and_b64 vcc, s[8:9], vcc
	v_add_u32_e32 v146, 0xffffff88, v143
	v_add_u32_e32 v147, -13, v141
	v_cndmask_b32_e32 v53, v176, v53, vcc
	v_cmp_gt_i32_e32 vcc, s93, v147
	v_cmp_le_i32_e64 s[8:9], v146, v114
	s_and_b64 vcc, s[8:9], vcc
	v_cndmask_b32_e32 v148, v176, v54, vcc
	v_add_u32_e32 v54, 0xffffff89, v143
	v_add_u32_e32 v146, -14, v141
	v_cmp_gt_i32_e32 vcc, s93, v146
	v_cmp_le_i32_e64 s[8:9], v54, v114
	v_max3_f32 v145, v50, s94, v51
	s_and_b64 vcc, s[8:9], vcc
	v_max3_f32 v145, v145, v52, v53
	v_cndmask_b32_e32 v147, v176, v55, vcc
	v_max3_f32 v54, v145, v148, v147
	v_add_u32_e32 v55, 0xffffff8a, v143
	v_add_u32_e32 v145, -15, v141
	v_cmp_gt_i32_e32 vcc, s93, v145
	v_cmp_le_i32_e64 s[8:9], v55, v114
	s_and_b64 vcc, s[8:9], vcc
	v_cndmask_b32_e32 v149, v176, v56, vcc
	v_add_u32_e32 v55, 0xffffff8b, v143
	v_add_u32_e32 v56, -16, v141
	v_cmp_gt_i32_e32 vcc, s93, v56
	v_cmp_le_i32_e64 s[8:9], v55, v114
	s_and_b64 vcc, s[8:9], vcc
	v_add_u32_e32 v55, 0xffffff90, v143
	v_subrev_u32_e32 v56, 21, v141
	v_cndmask_b32_e32 v150, v176, v57, vcc
	v_cmp_gt_i32_e32 vcc, s93, v56
	v_cmp_le_i32_e64 s[8:9], v55, v114
	s_and_b64 vcc, s[8:9], vcc
	v_add_u32_e32 v55, 0xffffff91, v143
	v_subrev_u32_e32 v56, 22, v141
	v_cndmask_b32_e32 v151, v176, v58, vcc
	v_cmp_gt_i32_e32 vcc, s93, v56
	v_cmp_le_i32_e64 s[8:9], v55, v114
	s_and_b64 vcc, s[8:9], vcc
	v_add_u32_e32 v55, 0xffffff92, v143
	v_subrev_u32_e32 v56, 23, v141
	v_cndmask_b32_e32 v145, v176, v59, vcc
	v_cmp_gt_i32_e32 vcc, s93, v56
	v_cmp_le_i32_e64 s[8:9], v55, v114
	s_and_b64 vcc, s[8:9], vcc
	v_add_u32_e32 v55, 0xffffff93, v143
	v_subrev_u32_e32 v56, 24, v141
	v_cndmask_b32_e32 v146, v176, v60, vcc
	v_cmp_gt_i32_e32 vcc, s93, v56
	v_cmp_le_i32_e64 s[8:9], v55, v114
	s_and_b64 vcc, s[8:9], vcc
	v_add_u32_e32 v55, 0xffffff98, v143
	v_subrev_u32_e32 v56, 29, v141
	v_cndmask_b32_e32 v60, v176, v61, vcc
	v_cmp_gt_i32_e32 vcc, s93, v56
	v_cmp_le_i32_e64 s[8:9], v55, v114
	s_and_b64 vcc, s[8:9], vcc
	v_add_u32_e32 v55, 0xffffff99, v143
	v_subrev_u32_e32 v56, 30, v141
	v_cndmask_b32_e32 v61, v176, v62, vcc
	v_cmp_gt_i32_e32 vcc, s93, v56
	v_cmp_le_i32_e64 s[8:9], v55, v114
	s_and_b64 vcc, s[8:9], vcc
	v_add_u32_e32 v55, 0xffffff9a, v143
	v_subrev_u32_e32 v56, 31, v141
	v_cndmask_b32_e32 v58, v176, v63, vcc
	v_cmp_gt_i32_e32 vcc, s93, v56
	v_cmp_le_i32_e64 s[8:9], v55, v114
	v_max3_f32 v54, v54, v149, v150
	s_and_b64 vcc, s[8:9], vcc
	v_add_u32_e32 v55, 0xffffff9b, v143
	v_subrev_u32_e32 v56, 32, v141
	v_max3_f32 v54, v54, v151, v145
	v_cndmask_b32_e32 v59, v176, v64, vcc
	v_cmp_gt_i32_e32 vcc, s93, v56
	v_cmp_le_i32_e64 s[8:9], v55, v114
	v_max3_f32 v54, v54, v146, v60
	s_and_b64 vcc, s[8:9], vcc
	v_max3_f32 v54, v54, v61, v58
	v_cndmask_b32_e32 v56, v176, v65, vcc
; template <int DQK, bool WIN>
; DI void attn_item(const u16* __restrict__ Qb, int ldq, const u16* __restrict__ Kb, int ldk, const u16* __restrict__ Vtb, int qb,
;                   float qscale, float sink2, const u16* __restrict__ zb, int ldz, u16* __restrict__ ob, int ldo, u16* lds) {
;     ...
;           if (MASK) {
;             int kg = k0 + kb * 32 + (i & 3) + 8 * (i >> 2) + 4 * hh;
;             bool ok = kg <= qrow;
;             if (WIN) ok = ok && (qrow - kg < 128);
;             v = ok ? v : -INFINITY;
;             st[kb][i] = v;
;           }
;           mx = fmaxf(mx, v);
;         }
;       mx = fmaxf(mx, __shfl_xor(mx, 32));
;       const float mn = fmaxf(m, mx);
;       if (__any(mn != m)) {
;         const float alpha = __builtin_amdgcn_exp2f((m - mn) * qscale);
;         lsum *= alpha;
; #pragma unroll
;         for (int i = 0; i < 16; ++i) { o[0][i] *= alpha; o[1][i] *= alpha; }
;       }
	v_max3_f32 v55, v54, v59, v56
	v_add_u32_e32 v54, 0xffffffa0, v143
	v_subrev_u32_e32 v57, 37, v141
	v_cmp_gt_i32_e32 vcc, s93, v57
	v_cmp_le_i32_e64 s[8:9], v54, v114
	s_and_b64 vcc, s[8:9], vcc
	v_cndmask_b32_e32 v57, v176, v34, vcc
	v_add_u32_e32 v34, 0xffffffa1, v143
	v_subrev_u32_e32 v54, 38, v141
	v_cmp_gt_i32_e32 vcc, s93, v54
	v_cmp_le_i32_e64 s[8:9], v34, v114
	s_and_b64 vcc, s[8:9], vcc
	v_cndmask_b32_e32 v54, v176, v35, vcc
	v_max3_f32 v34, v55, v57, v54
	v_add_u32_e32 v35, 0xffffffa2, v143
	v_subrev_u32_e32 v55, 39, v141
	v_cmp_gt_i32_e32 vcc, s93, v55
	v_cmp_le_i32_e64 s[8:9], v35, v114
	s_and_b64 vcc, s[8:9], vcc
	v_cndmask_b32_e32 v55, v176, v36, vcc
	v_add_u32_e32 v35, 0xffffffa3, v143
	v_subrev_u32_e32 v36, 40, v141
	v_cmp_gt_i32_e32 vcc, s93, v36
	v_cmp_le_i32_e64 s[8:9], v35, v114
	s_and_b64 vcc, s[8:9], vcc
	v_cndmask_b32_e32 v36, v176, v37, vcc
	v_add_u32_e32 v35, 0xffffffa8, v143
	v_subrev_u32_e32 v37, 45, v141
	v_cmp_gt_i32_e32 vcc, s93, v37
	v_cmp_le_i32_e64 s[8:9], v35, v114
	s_and_b64 vcc, s[8:9], vcc
	v_cndmask_b32_e32 v37, v176, v38, vcc
	v_add_u32_e32 v35, 0xffffffa9, v143
	v_subrev_u32_e32 v38, 46, v141
	v_cmp_gt_i32_e32 vcc, s93, v38
	v_cmp_le_i32_e64 s[8:9], v35, v114
	s_and_b64 vcc, s[8:9], vcc
	v_cndmask_b32_e32 v35, v176, v39, vcc
	v_add_u32_e32 v38, 0xffffffaa, v143
	v_subrev_u32_e32 v39, 47, v141
	v_cmp_gt_i32_e32 vcc, s93, v39
	v_cmp_le_i32_e64 s[8:9], v38, v114
	s_and_b64 vcc, s[8:9], vcc
	v_cndmask_b32_e32 v38, v176, v40, vcc
	v_add_u32_e32 v39, 0xffffffab, v143
	v_subrev_u32_e32 v40, 48, v141
	v_cmp_gt_i32_e32 vcc, s93, v40
	v_cmp_le_i32_e64 s[8:9], v39, v114
	s_and_b64 vcc, s[8:9], vcc
	v_cndmask_b32_e32 v39, v176, v41, vcc
	v_add_u32_e32 v40, 0xffffffb0, v143
	v_subrev_u32_e32 v41, 53, v141
	v_cmp_gt_i32_e32 vcc, s93, v41
	v_cmp_le_i32_e64 s[8:9], v40, v114
	s_and_b64 vcc, s[8:9], vcc
	v_cndmask_b32_e32 v40, v176, v42, vcc
	v_add_u32_e32 v41, 0xffffffb1, v143
	v_subrev_u32_e32 v42, 54, v141
	v_cmp_gt_i32_e32 vcc, s93, v42
	v_cmp_le_i32_e64 s[8:9], v41, v114
	s_and_b64 vcc, s[8:9], vcc
	v_cndmask_b32_e32 v41, v176, v43, vcc
	v_add_u32_e32 v42, 0xffffffb2, v143
	v_subrev_u32_e32 v43, 55, v141
	v_cmp_gt_i32_e32 vcc, s93, v43
	v_cmp_le_i32_e64 s[8:9], v42, v114
	s_and_b64 vcc, s[8:9], vcc
	v_cndmask_b32_e32 v42, v176, v44, vcc
	v_add_u32_e32 v43, 0xffffffb3, v143
	v_subrev_u32_e32 v44, 56, v141
	v_cmp_gt_i32_e32 vcc, s93, v44
	v_cmp_le_i32_e64 s[8:9], v43, v114
	s_and_b64 vcc, s[8:9], vcc
	v_cndmask_b32_e32 v43, v176, v45, vcc
	v_add_u32_e32 v44, 0xffffffb8, v143
	v_subrev_u32_e32 v45, 61, v141
	v_cmp_gt_i32_e32 vcc, s93, v45
	v_cmp_le_i32_e64 s[8:9], v44, v114
	s_and_b64 vcc, s[8:9], vcc
	v_cndmask_b32_e32 v44, v176, v46, vcc
	v_add_u32_e32 v45, 0xffffffb9, v143
	v_subrev_u32_e32 v46, 62, v141
	v_cmp_gt_i32_e32 vcc, s93, v46
	v_cmp_le_i32_e64 s[8:9], v45, v114
	s_and_b64 vcc, s[8:9], vcc
	v_cndmask_b32_e32 v45, v176, v47, vcc
	v_add_u32_e32 v46, 0xffffffba, v143
	v_subrev_u32_e32 v47, 63, v141
	v_cmp_gt_i32_e32 vcc, s93, v47
	v_cmp_le_i32_e64 s[8:9], v46, v114
	s_and_b64 vcc, s[8:9], vcc
	v_cndmask_b32_e32 v46, v176, v48, vcc
	v_add_u32_e32 v47, 0xffffffbb, v143
	v_subrev_u32_e32 v48, 64, v141
	v_max3_f32 v34, v34, v55, v36
	v_cmp_gt_i32_e32 vcc, s93, v48
	v_cmp_le_i32_e64 s[8:9], v47, v114
	v_max3_f32 v34, v34, v37, v35
	s_and_b64 vcc, s[8:9], vcc
	v_max3_f32 v34, v34, v38, v39
	v_cndmask_b32_e32 v47, v176, v49, vcc
	v_max3_f32 v34, v34, v40, v41
	v_max3_f32 v34, v34, v42, v43
	v_max3_f32 v34, v34, v44, v45
	v_max3_f32 v34, v34, v46, v47
	v_mov_b32_e32 v48, v34
	s_nop 1
	v_permlane32_swap_b32 v48, v34
	s_waitcnt lgkmcnt(0)
	v_max3_f32 v34, v144, v34, v48
	v_cmp_neq_f32_e32 vcc, v34, v144
	s_cbranch_vccz .LBB0_326
	v_sub_f32_e32 v48, v144, v34
	v_mul_f32_e32 v48, 0x3e38aa3b, v48
	v_exp_f32_e32 v48, v48
	s_nop 0
	v_mul_f32_e32 v116, v116, v48
	v_pk_mul_f32 v[32:33], v[32:33], v[48:49] op_sel_hi:[1,0]
	v_pk_mul_f32 v[30:31], v[30:31], v[48:49] op_sel_hi:[1,0]
	v_pk_mul_f32 v[28:29], v[28:29], v[48:49] op_sel_hi:[1,0]
	v_pk_mul_f32 v[26:27], v[26:27], v[48:49] op_sel_hi:[1,0]
	v_pk_mul_f32 v[24:25], v[24:25], v[48:49] op_sel_hi:[1,0]
	v_pk_mul_f32 v[22:23], v[22:23], v[48:49] op_sel_hi:[1,0]
	v_pk_mul_f32 v[20:21], v[20:21], v[48:49] op_sel_hi:[1,0]
	v_pk_mul_f32 v[18:19], v[18:19], v[48:49] op_sel_hi:[1,0]
	v_pk_mul_f32 v[16:17], v[16:17], v[48:49] op_sel_hi:[1,0]
	v_pk_mul_f32 v[14:15], v[14:15], v[48:49] op_sel_hi:[1,0]
	v_pk_mul_f32 v[12:13], v[12:13], v[48:49] op_sel_hi:[1,0]
	v_pk_mul_f32 v[10:11], v[10:11], v[48:49] op_sel_hi:[1,0]
	v_pk_mul_f32 v[8:9], v[8:9], v[48:49] op_sel_hi:[1,0]
	v_pk_mul_f32 v[6:7], v[6:7], v[48:49] op_sel_hi:[1,0]
	v_pk_mul_f32 v[4:5], v[4:5], v[48:49] op_sel_hi:[1,0]
	v_pk_mul_f32 v[2:3], v[2:3], v[48:49] op_sel_hi:[1,0]
